# out-proj->MLP-in seam: the first XCC arriver does the L2 writeback while the others are still arriving; the last arriver only confirms it and signals the cross-XCD arrival
# baseline (speedup 1.0000x reference)
; __device__ __forceinline__ unsigned xb_add(unsigned* p, unsigned v) { return __hip_atomic_fetch_add(p, v, __ATOMIC_RELAXED, __HIP_MEMORY_SCOPE_AGENT); }
; __device__ __forceinline__ void xcd_barrier(const XcdBarrier& b) {
;     ...
;         const unsigned old = xb_add(&bar[XB_XSUB(b.x)], 1u);
;         const unsigned gen = old / nloc;
;         if (old + 1u == (gen + 1u) * nloc) {
.LBB0_1016:
	s_or_b64 exec, exec, s[4:5]
	v_cvt_f32_u32_e32 v4, v2
	s_waitcnt vmcnt(0)
	v_readfirstlane_b32 s4, v3
	v_sub_u32_e32 v3, 0, v2
	v_rcp_iflag_f32_e32 v4, v4
	v_add_u32_e32 v5, s4, v1
	v_mul_f32_e32 v4, 0x4f7ffffe, v4
	v_cvt_u32_f32_e32 v4, v4
	v_mul_lo_u32 v1, v3, v4
	v_mul_hi_u32 v1, v4, v1
	v_add_u32_e32 v1, v4, v1
	v_mul_hi_u32 v1, v5, v1
	v_mul_lo_u32 v3, v1, v2
	v_sub_u32_e32 v3, v5, v3
	v_add_u32_e32 v4, 1, v1
	v_cmp_ge_u32_e32 vcc, v3, v2
	s_nop 1
	v_cndmask_b32_e32 v1, v1, v4, vcc
	v_sub_u32_e32 v4, v3, v2
	v_cndmask_b32_e32 v3, v3, v4, vcc
	v_add_u32_e32 v4, 1, v1
	v_cmp_ge_u32_e32 vcc, v3, v2
	v_add_u32_e32 v3, 1, v5
	s_nop 0
	v_cndmask_b32_e32 v1, v1, v4, vcc
	v_mul_lo_u32 v4, v2, v1
	v_add_u32_e32 v2, v4, v2
	v_cmp_ne_u32_e32 vcc, v5, v4
	s_cbranch_vccnz .Lg1_notfirst
	v_mov_b32_e32 v8, 0x20000
	ds_read_b32 v9, v8 offset:40
	s_waitcnt lgkmcnt(0)
	v_cmp_eq_u32_e32 vcc, 0, v9
	s_cbranch_vccnz .Lg1_notfirst
	buffer_wbl2 sc1
	s_waitcnt vmcnt(0)
	v_readlane_b32 s6, v253, 38
	v_readlane_b32 s7, v253, 39
	v_mov_b32_e32 v8, 0x80
	v_mov_b32_e32 v9, 1
	s_nop 3
	global_atomic_add v8, v9, s[6:7]
.Lg1_notfirst:
	v_cmp_ne_u32_e32 vcc, v3, v2
	s_and_saveexec_b64 s[4:5], vcc
	s_xor_b64 s[4:5], exec, s[4:5]
	s_cbranch_execz .LBB0_1030
	v_readlane_b32 s6, v253, 40
	v_readlane_b32 s7, v253, 41
	s_waitcnt lgkmcnt(0)
	s_nop 3
	global_load_dword v0, v181, s[6:7] sc1
	s_waitcnt vmcnt(0)
	v_cmp_eq_u32_e32 vcc, v0, v1
	s_and_saveexec_b64 s[6:7], vcc
	s_cbranch_execz .LBB0_1029
	s_mov_b32 s13, 1
	s_mov_b64 s[28:29], 0
	s_branch .LBB0_1020

; __device__ __forceinline__ unsigned xb_ld(unsigned* p)              { return __hip_atomic_load(p, __ATOMIC_RELAXED, __HIP_MEMORY_SCOPE_AGENT); }
; __device__ __forceinline__ unsigned xb_add(unsigned* p, unsigned v) { return __hip_atomic_fetch_add(p, v, __ATOMIC_RELAXED, __HIP_MEMORY_SCOPE_AGENT); }
; #define XB_SPIN(cond, bar) do { unsigned _sp = 0; while (cond) { __builtin_amdgcn_s_sleep(1); \
;     if ((++_sp & 255u) == 0u) { if (xb_ld(&(bar)[XB_TMO])) break; if (_sp > XB_SPIN_CAP) { atomicAdd(&(bar)[XB_TMO], 1u); break; } } } } while (0)
; __device__ __forceinline__ void xcd_barrier(const XcdBarrier& b) {
;     ...
;         if (old + 1u == (gen + 1u) * nloc) {
;             __builtin_amdgcn_fence(__ATOMIC_RELEASE, "agent");
;             asm volatile("s_waitcnt vmcnt(0)" ::: "memory");
;             const unsigned og = xb_add(&bar[XB_TOP], 1u);
;             const unsigned tg = og / nx;
;             if (og + 1u == (tg + 1u) * nx) xb_add(&bar[XB_TOPGEN], 1u);
;             else XB_SPIN(xb_ld(&bar[XB_TOPGEN]) == tg, bar);
;             __builtin_amdgcn_fence(__ATOMIC_ACQUIRE, "agent");
;             xb_add(&bar[XB_XGEN(b.x)], 1u);
;             asm volatile("s_waitcnt vmcnt(0)" ::: "memory");
.LBB0_1030:
	s_andn2_saveexec_b64 s[4:5], s[4:5]
	s_cbranch_execz .LBB0_1050
	s_mov_b64 s[4:5], exec
	v_mov_b32_e32 v1, 0x20000
	ds_read_b32 v2, v1 offset:40
	s_waitcnt lgkmcnt(0)
	v_cmp_eq_u32_e32 vcc, 0, v2
	s_cbranch_vccnz .Lxb_gfull_3
	ds_read_b64 v[2:3], v1 offset:64
	ds_read_b32 v4, v1 offset:48
	v_readlane_b32 s4, v253, 38
	v_readlane_b32 s5, v253, 39
	v_mov_b32_e32 v5, 0x80
	v_mov_b32_e32 v7, 0
	s_waitcnt lgkmcnt(0)
	s_nop 4
.Lg1_flspin:
	global_load_dword v6, v5, s[4:5] sc1
	v_add_u32_e32 v7, 1, v7
	s_waitcnt vmcnt(0)
	v_cmp_gt_u32_e32 vcc, v6, v4
	s_cbranch_vccnz .Lg1_fldone
	v_cmp_lt_u32_e32 vcc, 0x40000, v7
	s_cbranch_vccnz .Lg1_fldone
	s_sleep 1
	s_branch .Lg1_flspin
.Lg1_fldone:
	v_mov_b32_e32 v1, 1
	global_atomic_add v[2:3], v1, off
	s_branch .Lxb_local_3
